# combo18 + E62: phase-0 adaLN GEMV issues all 32 weight loads of a thread up front instead of 4 dependent batches of 8 (same FMAs, same order)
# speedup vs baseline: 1.0077x; 1.0065x over previous
.LBB0_432:
	s_or_b64 exec, exec, s[12:13]
	s_and_saveexec_b64 s[12:13], s[38:39]
	s_cbranch_execz .LBB0_436
	v_readlane_b32 s84, v254, 4
	v_readlane_b32 s90, v254, 10
	v_readlane_b32 s91, v254, 11
	v_add_u32_e32 v12, 0xe0, v26
	s_movk_i32 s18, 0x3000
	v_mov_b64_e32 v[36:37], s[90:91]
	v_add_u32_e32 v14, 0xc0, v26
	v_add_u32_e32 v16, 0xa0, v26
	v_add_u32_e32 v18, 0x80, v26
	v_add_u32_e32 v20, 0x60, v26
	v_add_u32_e32 v22, 64, v26
	v_add_u32_e32 v24, 32, v26
	v_add_u32_e32 v9, 0xffffff00, v26
	v_mad_i64_i32 v[12:13], s[14:15], v12, s18, v[36:37]
	v_mad_i64_i32 v[14:15], s[14:15], v14, s18, v[36:37]
	v_mad_i64_i32 v[16:17], s[14:15], v16, s18, v[36:37]
	v_mad_i64_i32 v[18:19], s[14:15], v18, s18, v[36:37]
	v_mad_i64_i32 v[20:21], s[14:15], v20, s18, v[36:37]
	v_mad_i64_i32 v[22:23], s[14:15], v22, s18, v[36:37]
	v_mad_i64_i32 v[24:25], s[14:15], v24, s18, v[36:37]
	v_lshl_add_u32 v34, v26, 2, 16
	v_mad_i64_i32 v[26:27], s[14:15], v26, s18, v[36:37]
	s_mov_b64 s[14:15], 0
	v_readlane_b32 s85, v254, 5
	v_readlane_b32 s86, v254, 6
	v_readlane_b32 s87, v254, 7
	v_readlane_b32 s88, v254, 8
	v_readlane_b32 s89, v254, 9
	v_readlane_b32 s92, v254, 12
	v_readlane_b32 s93, v254, 13
	v_readlane_b32 s94, v254, 14
	v_readlane_b32 s95, v254, 15
	v_readlane_b32 s96, v254, 16
	v_readlane_b32 s97, v254, 17
	v_readlane_b32 s98, v254, 18
	v_readlane_b32 s99, v254, 19
	v_lshl_add_u64 v[36:37], v[26:27], 0, v[10:11]
	v_lshl_add_u64 v[38:39], v[24:25], 0, v[10:11]
	v_lshl_add_u64 v[40:41], v[22:23], 0, v[10:11]
	v_lshl_add_u64 v[42:43], v[20:21], 0, v[10:11]
	v_lshl_add_u64 v[44:45], v[18:19], 0, v[10:11]
	v_lshl_add_u64 v[46:47], v[16:17], 0, v[10:11]
	v_lshl_add_u64 v[48:49], v[14:15], 0, v[10:11]
	v_lshl_add_u64 v[50:51], v[12:13], 0, v[10:11]
	global_load_dword v88, v[36:37], off
	s_nop 0
	global_load_dword v90, v[38:39], off
	s_nop 0
	global_load_dword v92, v[40:41], off
	s_nop 0
	global_load_dword v94, v[42:43], off
	s_nop 0
	global_load_dword v96, v[44:45], off
	s_nop 0
	global_load_dword v98, v[46:47], off
	s_nop 0
	global_load_dword v100, v[48:49], off
	s_nop 0
	global_load_dword v102, v[50:51], off
	s_nop 0
	v_lshl_add_u64 v[12:13], v[12:13], 0, s[2:3]
	v_lshl_add_u64 v[14:15], v[14:15], 0, s[2:3]
	v_lshl_add_u64 v[16:17], v[16:17], 0, s[2:3]
	v_lshl_add_u64 v[18:19], v[18:19], 0, s[2:3]
	v_lshl_add_u64 v[20:21], v[20:21], 0, s[2:3]
	v_lshl_add_u64 v[22:23], v[22:23], 0, s[2:3]
	v_lshl_add_u64 v[24:25], v[24:25], 0, s[2:3]
	v_lshl_add_u64 v[26:27], v[26:27], 0, s[2:3]
	v_lshl_add_u64 v[36:37], v[26:27], 0, v[10:11]
	v_lshl_add_u64 v[38:39], v[24:25], 0, v[10:11]
	v_lshl_add_u64 v[40:41], v[22:23], 0, v[10:11]
	v_lshl_add_u64 v[42:43], v[20:21], 0, v[10:11]
	v_lshl_add_u64 v[44:45], v[18:19], 0, v[10:11]
	v_lshl_add_u64 v[46:47], v[16:17], 0, v[10:11]
	v_lshl_add_u64 v[48:49], v[14:15], 0, v[10:11]
	v_lshl_add_u64 v[50:51], v[12:13], 0, v[10:11]
	global_load_dword v104, v[36:37], off
	s_nop 0
	global_load_dword v106, v[38:39], off
	s_nop 0
	global_load_dword v108, v[40:41], off
	s_nop 0
	global_load_dword v110, v[42:43], off
	s_nop 0
	global_load_dword v112, v[44:45], off
	s_nop 0
	global_load_dword v114, v[46:47], off
	s_nop 0
	global_load_dword v116, v[48:49], off
	s_nop 0
	global_load_dword v118, v[50:51], off
	s_nop 0
	v_lshl_add_u64 v[12:13], v[12:13], 0, s[2:3]
	v_lshl_add_u64 v[14:15], v[14:15], 0, s[2:3]
	v_lshl_add_u64 v[16:17], v[16:17], 0, s[2:3]
	v_lshl_add_u64 v[18:19], v[18:19], 0, s[2:3]
	v_lshl_add_u64 v[20:21], v[20:21], 0, s[2:3]
	v_lshl_add_u64 v[22:23], v[22:23], 0, s[2:3]
	v_lshl_add_u64 v[24:25], v[24:25], 0, s[2:3]
	v_lshl_add_u64 v[26:27], v[26:27], 0, s[2:3]
	v_lshl_add_u64 v[36:37], v[26:27], 0, v[10:11]
	v_lshl_add_u64 v[38:39], v[24:25], 0, v[10:11]
	v_lshl_add_u64 v[40:41], v[22:23], 0, v[10:11]
	v_lshl_add_u64 v[42:43], v[20:21], 0, v[10:11]
	v_lshl_add_u64 v[44:45], v[18:19], 0, v[10:11]
	v_lshl_add_u64 v[46:47], v[16:17], 0, v[10:11]
	v_lshl_add_u64 v[48:49], v[14:15], 0, v[10:11]
	v_lshl_add_u64 v[50:51], v[12:13], 0, v[10:11]
	global_load_dword v120, v[36:37], off
	s_nop 0
	global_load_dword v122, v[38:39], off
	s_nop 0
	global_load_dword v124, v[40:41], off
	s_nop 0
	global_load_dword v126, v[42:43], off
	s_nop 0
	global_load_dword v128, v[44:45], off
	s_nop 0
	global_load_dword v130, v[46:47], off
	s_nop 0
	global_load_dword v132, v[48:49], off
	s_nop 0
	global_load_dword v134, v[50:51], off
	s_nop 0
	v_lshl_add_u64 v[12:13], v[12:13], 0, s[2:3]
	v_lshl_add_u64 v[14:15], v[14:15], 0, s[2:3]
	v_lshl_add_u64 v[16:17], v[16:17], 0, s[2:3]
	v_lshl_add_u64 v[18:19], v[18:19], 0, s[2:3]
	v_lshl_add_u64 v[20:21], v[20:21], 0, s[2:3]
	v_lshl_add_u64 v[22:23], v[22:23], 0, s[2:3]
	v_lshl_add_u64 v[24:25], v[24:25], 0, s[2:3]
	v_lshl_add_u64 v[26:27], v[26:27], 0, s[2:3]
	v_lshl_add_u64 v[36:37], v[26:27], 0, v[10:11]
	v_lshl_add_u64 v[38:39], v[24:25], 0, v[10:11]
	v_lshl_add_u64 v[40:41], v[22:23], 0, v[10:11]
	v_lshl_add_u64 v[42:43], v[20:21], 0, v[10:11]
	v_lshl_add_u64 v[44:45], v[18:19], 0, v[10:11]
	v_lshl_add_u64 v[46:47], v[16:17], 0, v[10:11]
	v_lshl_add_u64 v[48:49], v[14:15], 0, v[10:11]
	v_lshl_add_u64 v[50:51], v[12:13], 0, v[10:11]
	global_load_dword v136, v[36:37], off
	s_nop 0
	global_load_dword v138, v[38:39], off
	s_nop 0
	global_load_dword v140, v[40:41], off
	s_nop 0
	global_load_dword v142, v[42:43], off
	s_nop 0
	global_load_dword v144, v[44:45], off
	s_nop 0
	global_load_dword v146, v[46:47], off
	s_nop 0
	global_load_dword v148, v[48:49], off
	s_nop 0
	global_load_dword v150, v[50:51], off
	s_nop 0
	v_lshl_add_u64 v[12:13], v[12:13], 0, s[2:3]
	v_lshl_add_u64 v[14:15], v[14:15], 0, s[2:3]
	v_lshl_add_u64 v[16:17], v[16:17], 0, s[2:3]
	v_lshl_add_u64 v[18:19], v[18:19], 0, s[2:3]
	v_lshl_add_u64 v[20:21], v[20:21], 0, s[2:3]
	v_lshl_add_u64 v[22:23], v[22:23], 0, s[2:3]
	v_lshl_add_u64 v[24:25], v[24:25], 0, s[2:3]
	v_lshl_add_u64 v[26:27], v[26:27], 0, s[2:3]
	ds_read2_b32 v[52:53], v34 offset1:32
	v_add_u32_e32 v35, 0x1000, v34
	ds_read2_b32 v[54:55], v34 offset0:64 offset1:96
	ds_read2_b32 v[56:57], v34 offset0:128 offset1:160
	ds_read2_b32 v[58:59], v34 offset0:192 offset1:224
	v_add_u32_e32 v37, 0x2000, v34
	v_add_u32_e32 v39, 0x3000, v34
	ds_read2_b32 v[60:61], v35 offset1:32
	ds_read2_b32 v[62:63], v37 offset1:32
	ds_read2_b32 v[64:65], v39 offset1:32
	ds_read2_b32 v[66:67], v35 offset0:64 offset1:96
	ds_read2_b32 v[68:69], v37 offset0:64 offset1:96
	ds_read2_b32 v[70:71], v39 offset0:64 offset1:96
	ds_read2_b32 v[72:73], v35 offset0:128 offset1:160
	ds_read2_b32 v[74:75], v37 offset0:128 offset1:160
	ds_read2_b32 v[76:77], v39 offset0:128 offset1:160
	ds_read2_b32 v[78:79], v35 offset0:192 offset1:224
	ds_read2_b32 v[80:81], v37 offset0:192 offset1:224
	ds_read2_b32 v[82:83], v39 offset0:192 offset1:224
	s_waitcnt lgkmcnt(14)
	v_mov_b32_e32 v84, v52
	s_waitcnt lgkmcnt(11)
	v_mov_b32_e32 v85, v60
	s_waitcnt lgkmcnt(10)
	v_mov_b32_e32 v86, v62
	s_waitcnt lgkmcnt(9)
	v_mov_b32_e32 v87, v64
	v_mov_b32_e32 v60, v53
	v_mov_b32_e32 v64, v63
	v_mov_b32_e32 v52, v54
	s_waitcnt lgkmcnt(8)
	v_mov_b32_e32 v53, v66
	s_waitcnt lgkmcnt(7)
	v_mov_b32_e32 v62, v68
	s_waitcnt lgkmcnt(6)
	v_mov_b32_e32 v63, v70
	v_mov_b32_e32 v66, v55
	v_mov_b32_e32 v70, v69
	v_mov_b32_e32 v54, v56
	s_waitcnt lgkmcnt(5)
	v_mov_b32_e32 v55, v72
	s_waitcnt lgkmcnt(4)
	v_mov_b32_e32 v68, v74
	s_waitcnt lgkmcnt(3)
	v_mov_b32_e32 v69, v76
	v_mov_b32_e32 v72, v57
	v_mov_b32_e32 v76, v75
	v_mov_b32_e32 v56, v58
	s_waitcnt lgkmcnt(2)
	v_mov_b32_e32 v57, v78
	s_waitcnt lgkmcnt(1)
	v_mov_b32_e32 v74, v80
	s_waitcnt lgkmcnt(0)
	v_mov_b32_e32 v75, v82
	v_mov_b32_e32 v78, v59
	v_mov_b32_e32 v82, v81
	v_add_u32_e32 v34, 0x400, v34
	s_waitcnt vmcnt(31)
	v_pk_fma_f32 v[0:1], v[88:89], v[84:85], v[0:1] op_sel_hi:[0,1,1]
	v_pk_fma_f32 v[2:3], v[88:89], v[86:87], v[2:3] op_sel_hi:[0,1,1]
	s_waitcnt vmcnt(30)
	v_pk_fma_f32 v[0:1], v[90:91], v[60:61], v[0:1] op_sel_hi:[0,1,1]
	v_pk_fma_f32 v[2:3], v[90:91], v[64:65], v[2:3] op_sel_hi:[0,1,1]
	s_waitcnt vmcnt(29)
	v_pk_fma_f32 v[0:1], v[92:93], v[52:53], v[0:1] op_sel_hi:[0,1,1]
	v_pk_fma_f32 v[2:3], v[92:93], v[62:63], v[2:3] op_sel_hi:[0,1,1]
	s_waitcnt vmcnt(28)
	v_pk_fma_f32 v[0:1], v[94:95], v[66:67], v[0:1] op_sel_hi:[0,1,1]
	v_pk_fma_f32 v[2:3], v[94:95], v[70:71], v[2:3] op_sel_hi:[0,1,1]
	s_waitcnt vmcnt(27)
	v_pk_fma_f32 v[0:1], v[96:97], v[54:55], v[0:1] op_sel_hi:[0,1,1]
	v_pk_fma_f32 v[2:3], v[96:97], v[68:69], v[2:3] op_sel_hi:[0,1,1]
	s_waitcnt vmcnt(26)
	v_pk_fma_f32 v[0:1], v[98:99], v[72:73], v[0:1] op_sel_hi:[0,1,1]
	v_pk_fma_f32 v[2:3], v[98:99], v[76:77], v[2:3] op_sel_hi:[0,1,1]
	s_waitcnt vmcnt(25)
	v_pk_fma_f32 v[0:1], v[100:101], v[56:57], v[0:1] op_sel_hi:[0,1,1]
	v_pk_fma_f32 v[2:3], v[100:101], v[74:75], v[2:3] op_sel_hi:[0,1,1]
	s_waitcnt vmcnt(24)
	v_pk_fma_f32 v[0:1], v[102:103], v[78:79], v[0:1] op_sel_hi:[0,1,1]
	v_pk_fma_f32 v[2:3], v[102:103], v[82:83], v[2:3] op_sel_hi:[0,1,1]
	ds_read2_b32 v[52:53], v34 offset1:32
	v_add_u32_e32 v35, 0x1000, v34
	ds_read2_b32 v[54:55], v34 offset0:64 offset1:96
	ds_read2_b32 v[56:57], v34 offset0:128 offset1:160
	ds_read2_b32 v[58:59], v34 offset0:192 offset1:224
	v_add_u32_e32 v37, 0x2000, v34
	v_add_u32_e32 v39, 0x3000, v34
	ds_read2_b32 v[60:61], v35 offset1:32
	ds_read2_b32 v[62:63], v37 offset1:32
	ds_read2_b32 v[64:65], v39 offset1:32
	ds_read2_b32 v[66:67], v35 offset0:64 offset1:96
	ds_read2_b32 v[68:69], v37 offset0:64 offset1:96
	ds_read2_b32 v[70:71], v39 offset0:64 offset1:96
	ds_read2_b32 v[72:73], v35 offset0:128 offset1:160
	ds_read2_b32 v[74:75], v37 offset0:128 offset1:160
	ds_read2_b32 v[76:77], v39 offset0:128 offset1:160
	ds_read2_b32 v[78:79], v35 offset0:192 offset1:224
	ds_read2_b32 v[80:81], v37 offset0:192 offset1:224
	ds_read2_b32 v[82:83], v39 offset0:192 offset1:224
	s_waitcnt lgkmcnt(14)
	v_mov_b32_e32 v84, v52
	s_waitcnt lgkmcnt(11)
	v_mov_b32_e32 v85, v60
	s_waitcnt lgkmcnt(10)
	v_mov_b32_e32 v86, v62
	s_waitcnt lgkmcnt(9)
	v_mov_b32_e32 v87, v64
	v_mov_b32_e32 v60, v53
	v_mov_b32_e32 v64, v63
	v_mov_b32_e32 v52, v54
	s_waitcnt lgkmcnt(8)
	v_mov_b32_e32 v53, v66
	s_waitcnt lgkmcnt(7)
	v_mov_b32_e32 v62, v68
	s_waitcnt lgkmcnt(6)
	v_mov_b32_e32 v63, v70
	v_mov_b32_e32 v66, v55
	v_mov_b32_e32 v70, v69
	v_mov_b32_e32 v54, v56
	s_waitcnt lgkmcnt(5)
	v_mov_b32_e32 v55, v72
	s_waitcnt lgkmcnt(4)
	v_mov_b32_e32 v68, v74
	s_waitcnt lgkmcnt(3)
	v_mov_b32_e32 v69, v76
	v_mov_b32_e32 v72, v57
	v_mov_b32_e32 v76, v75
	v_mov_b32_e32 v56, v58
	s_waitcnt lgkmcnt(2)
	v_mov_b32_e32 v57, v78
	s_waitcnt lgkmcnt(1)
	v_mov_b32_e32 v74, v80
	s_waitcnt lgkmcnt(0)
	v_mov_b32_e32 v75, v82
	v_mov_b32_e32 v78, v59
	v_mov_b32_e32 v82, v81
	v_add_u32_e32 v34, 0x400, v34
	s_waitcnt vmcnt(23)
	v_pk_fma_f32 v[0:1], v[104:105], v[84:85], v[0:1] op_sel_hi:[0,1,1]
	v_pk_fma_f32 v[2:3], v[104:105], v[86:87], v[2:3] op_sel_hi:[0,1,1]
	s_waitcnt vmcnt(22)
	v_pk_fma_f32 v[0:1], v[106:107], v[60:61], v[0:1] op_sel_hi:[0,1,1]
	v_pk_fma_f32 v[2:3], v[106:107], v[64:65], v[2:3] op_sel_hi:[0,1,1]
	s_waitcnt vmcnt(21)
	v_pk_fma_f32 v[0:1], v[108:109], v[52:53], v[0:1] op_sel_hi:[0,1,1]
	v_pk_fma_f32 v[2:3], v[108:109], v[62:63], v[2:3] op_sel_hi:[0,1,1]
	s_waitcnt vmcnt(20)
	v_pk_fma_f32 v[0:1], v[110:111], v[66:67], v[0:1] op_sel_hi:[0,1,1]
	v_pk_fma_f32 v[2:3], v[110:111], v[70:71], v[2:3] op_sel_hi:[0,1,1]
	s_waitcnt vmcnt(19)
	v_pk_fma_f32 v[0:1], v[112:113], v[54:55], v[0:1] op_sel_hi:[0,1,1]
	v_pk_fma_f32 v[2:3], v[112:113], v[68:69], v[2:3] op_sel_hi:[0,1,1]
	s_waitcnt vmcnt(18)
	v_pk_fma_f32 v[0:1], v[114:115], v[72:73], v[0:1] op_sel_hi:[0,1,1]
	v_pk_fma_f32 v[2:3], v[114:115], v[76:77], v[2:3] op_sel_hi:[0,1,1]
	s_waitcnt vmcnt(17)
	v_pk_fma_f32 v[0:1], v[116:117], v[56:57], v[0:1] op_sel_hi:[0,1,1]
	v_pk_fma_f32 v[2:3], v[116:117], v[74:75], v[2:3] op_sel_hi:[0,1,1]
	s_waitcnt vmcnt(16)
	v_pk_fma_f32 v[0:1], v[118:119], v[78:79], v[0:1] op_sel_hi:[0,1,1]
	v_pk_fma_f32 v[2:3], v[118:119], v[82:83], v[2:3] op_sel_hi:[0,1,1]
	ds_read2_b32 v[52:53], v34 offset1:32
	v_add_u32_e32 v35, 0x1000, v34
	ds_read2_b32 v[54:55], v34 offset0:64 offset1:96
	ds_read2_b32 v[56:57], v34 offset0:128 offset1:160
	ds_read2_b32 v[58:59], v34 offset0:192 offset1:224
	v_add_u32_e32 v37, 0x2000, v34
	v_add_u32_e32 v39, 0x3000, v34
	ds_read2_b32 v[60:61], v35 offset1:32
	ds_read2_b32 v[62:63], v37 offset1:32
	ds_read2_b32 v[64:65], v39 offset1:32
	ds_read2_b32 v[66:67], v35 offset0:64 offset1:96
	ds_read2_b32 v[68:69], v37 offset0:64 offset1:96
	ds_read2_b32 v[70:71], v39 offset0:64 offset1:96
	ds_read2_b32 v[72:73], v35 offset0:128 offset1:160
	ds_read2_b32 v[74:75], v37 offset0:128 offset1:160
	ds_read2_b32 v[76:77], v39 offset0:128 offset1:160
	ds_read2_b32 v[78:79], v35 offset0:192 offset1:224
	ds_read2_b32 v[80:81], v37 offset0:192 offset1:224
	ds_read2_b32 v[82:83], v39 offset0:192 offset1:224
	s_waitcnt lgkmcnt(14)
	v_mov_b32_e32 v84, v52
	s_waitcnt lgkmcnt(11)
	v_mov_b32_e32 v85, v60
	s_waitcnt lgkmcnt(10)
	v_mov_b32_e32 v86, v62
	s_waitcnt lgkmcnt(9)
	v_mov_b32_e32 v87, v64
	v_mov_b32_e32 v60, v53
	v_mov_b32_e32 v64, v63
	v_mov_b32_e32 v52, v54
	s_waitcnt lgkmcnt(8)
	v_mov_b32_e32 v53, v66
	s_waitcnt lgkmcnt(7)
	v_mov_b32_e32 v62, v68
	s_waitcnt lgkmcnt(6)
	v_mov_b32_e32 v63, v70
	v_mov_b32_e32 v66, v55
	v_mov_b32_e32 v70, v69
	v_mov_b32_e32 v54, v56
	s_waitcnt lgkmcnt(5)
	v_mov_b32_e32 v55, v72
	s_waitcnt lgkmcnt(4)
	v_mov_b32_e32 v68, v74
	s_waitcnt lgkmcnt(3)
	v_mov_b32_e32 v69, v76
	v_mov_b32_e32 v72, v57
	v_mov_b32_e32 v76, v75
	v_mov_b32_e32 v56, v58
	s_waitcnt lgkmcnt(2)
	v_mov_b32_e32 v57, v78
	s_waitcnt lgkmcnt(1)
	v_mov_b32_e32 v74, v80
	s_waitcnt lgkmcnt(0)
	v_mov_b32_e32 v75, v82
	v_mov_b32_e32 v78, v59
	v_mov_b32_e32 v82, v81
	v_add_u32_e32 v34, 0x400, v34
	s_waitcnt vmcnt(15)
	v_pk_fma_f32 v[0:1], v[120:121], v[84:85], v[0:1] op_sel_hi:[0,1,1]
	v_pk_fma_f32 v[2:3], v[120:121], v[86:87], v[2:3] op_sel_hi:[0,1,1]
	s_waitcnt vmcnt(14)
	v_pk_fma_f32 v[0:1], v[122:123], v[60:61], v[0:1] op_sel_hi:[0,1,1]
	v_pk_fma_f32 v[2:3], v[122:123], v[64:65], v[2:3] op_sel_hi:[0,1,1]
	s_waitcnt vmcnt(13)
	v_pk_fma_f32 v[0:1], v[124:125], v[52:53], v[0:1] op_sel_hi:[0,1,1]
	v_pk_fma_f32 v[2:3], v[124:125], v[62:63], v[2:3] op_sel_hi:[0,1,1]
	s_waitcnt vmcnt(12)
	v_pk_fma_f32 v[0:1], v[126:127], v[66:67], v[0:1] op_sel_hi:[0,1,1]
	v_pk_fma_f32 v[2:3], v[126:127], v[70:71], v[2:3] op_sel_hi:[0,1,1]
	s_waitcnt vmcnt(11)
	v_pk_fma_f32 v[0:1], v[128:129], v[54:55], v[0:1] op_sel_hi:[0,1,1]
	v_pk_fma_f32 v[2:3], v[128:129], v[68:69], v[2:3] op_sel_hi:[0,1,1]
	s_waitcnt vmcnt(10)
	v_pk_fma_f32 v[0:1], v[130:131], v[72:73], v[0:1] op_sel_hi:[0,1,1]
	v_pk_fma_f32 v[2:3], v[130:131], v[76:77], v[2:3] op_sel_hi:[0,1,1]
	s_waitcnt vmcnt(9)
	v_pk_fma_f32 v[0:1], v[132:133], v[56:57], v[0:1] op_sel_hi:[0,1,1]
	v_pk_fma_f32 v[2:3], v[132:133], v[74:75], v[2:3] op_sel_hi:[0,1,1]
	s_waitcnt vmcnt(8)
	v_pk_fma_f32 v[0:1], v[134:135], v[78:79], v[0:1] op_sel_hi:[0,1,1]
	v_pk_fma_f32 v[2:3], v[134:135], v[82:83], v[2:3] op_sel_hi:[0,1,1]
	ds_read2_b32 v[52:53], v34 offset1:32
	v_add_u32_e32 v35, 0x1000, v34
	ds_read2_b32 v[54:55], v34 offset0:64 offset1:96
	ds_read2_b32 v[56:57], v34 offset0:128 offset1:160
	ds_read2_b32 v[58:59], v34 offset0:192 offset1:224
	v_add_u32_e32 v37, 0x2000, v34
	v_add_u32_e32 v39, 0x3000, v34
	ds_read2_b32 v[60:61], v35 offset1:32
	ds_read2_b32 v[62:63], v37 offset1:32
	ds_read2_b32 v[64:65], v39 offset1:32
	ds_read2_b32 v[66:67], v35 offset0:64 offset1:96
	ds_read2_b32 v[68:69], v37 offset0:64 offset1:96
	ds_read2_b32 v[70:71], v39 offset0:64 offset1:96
	ds_read2_b32 v[72:73], v35 offset0:128 offset1:160
	ds_read2_b32 v[74:75], v37 offset0:128 offset1:160
	ds_read2_b32 v[76:77], v39 offset0:128 offset1:160
	ds_read2_b32 v[78:79], v35 offset0:192 offset1:224
	ds_read2_b32 v[80:81], v37 offset0:192 offset1:224
	ds_read2_b32 v[82:83], v39 offset0:192 offset1:224
	s_waitcnt lgkmcnt(14)
	v_mov_b32_e32 v84, v52
	s_waitcnt lgkmcnt(11)
	v_mov_b32_e32 v85, v60
	s_waitcnt lgkmcnt(10)
	v_mov_b32_e32 v86, v62
	s_waitcnt lgkmcnt(9)
	v_mov_b32_e32 v87, v64
	v_mov_b32_e32 v60, v53
	v_mov_b32_e32 v64, v63
	v_mov_b32_e32 v52, v54
	s_waitcnt lgkmcnt(8)
	v_mov_b32_e32 v53, v66
	s_waitcnt lgkmcnt(7)
	v_mov_b32_e32 v62, v68
	s_waitcnt lgkmcnt(6)
	v_mov_b32_e32 v63, v70
	v_mov_b32_e32 v66, v55
	v_mov_b32_e32 v70, v69
	v_mov_b32_e32 v54, v56
	s_waitcnt lgkmcnt(5)
	v_mov_b32_e32 v55, v72
	s_waitcnt lgkmcnt(4)
	v_mov_b32_e32 v68, v74
	s_waitcnt lgkmcnt(3)
	v_mov_b32_e32 v69, v76
	v_mov_b32_e32 v72, v57
	v_mov_b32_e32 v76, v75
	v_mov_b32_e32 v56, v58
	s_waitcnt lgkmcnt(2)
	v_mov_b32_e32 v57, v78
	s_waitcnt lgkmcnt(1)
	v_mov_b32_e32 v74, v80
	s_waitcnt lgkmcnt(0)
	v_mov_b32_e32 v75, v82
	v_mov_b32_e32 v78, v59
	v_mov_b32_e32 v82, v81
	v_add_u32_e32 v34, 0x400, v34
	s_waitcnt vmcnt(7)
	v_pk_fma_f32 v[0:1], v[136:137], v[84:85], v[0:1] op_sel_hi:[0,1,1]
	v_pk_fma_f32 v[2:3], v[136:137], v[86:87], v[2:3] op_sel_hi:[0,1,1]
	s_waitcnt vmcnt(6)
	v_pk_fma_f32 v[0:1], v[138:139], v[60:61], v[0:1] op_sel_hi:[0,1,1]
	v_pk_fma_f32 v[2:3], v[138:139], v[64:65], v[2:3] op_sel_hi:[0,1,1]
	s_waitcnt vmcnt(5)
	v_pk_fma_f32 v[0:1], v[140:141], v[52:53], v[0:1] op_sel_hi:[0,1,1]
	v_pk_fma_f32 v[2:3], v[140:141], v[62:63], v[2:3] op_sel_hi:[0,1,1]
	s_waitcnt vmcnt(4)
	v_pk_fma_f32 v[0:1], v[142:143], v[66:67], v[0:1] op_sel_hi:[0,1,1]
	v_pk_fma_f32 v[2:3], v[142:143], v[70:71], v[2:3] op_sel_hi:[0,1,1]
	s_waitcnt vmcnt(3)
	v_pk_fma_f32 v[0:1], v[144:145], v[54:55], v[0:1] op_sel_hi:[0,1,1]
	v_pk_fma_f32 v[2:3], v[144:145], v[68:69], v[2:3] op_sel_hi:[0,1,1]
	s_waitcnt vmcnt(2)
	v_pk_fma_f32 v[0:1], v[146:147], v[72:73], v[0:1] op_sel_hi:[0,1,1]
	v_pk_fma_f32 v[2:3], v[146:147], v[76:77], v[2:3] op_sel_hi:[0,1,1]
	s_waitcnt vmcnt(1)
	v_pk_fma_f32 v[0:1], v[148:149], v[56:57], v[0:1] op_sel_hi:[0,1,1]
	v_pk_fma_f32 v[2:3], v[148:149], v[74:75], v[2:3] op_sel_hi:[0,1,1]
	s_waitcnt vmcnt(0)
	v_pk_fma_f32 v[0:1], v[150:151], v[78:79], v[0:1] op_sel_hi:[0,1,1]
	v_pk_fma_f32 v[2:3], v[150:151], v[82:83], v[2:3] op_sel_hi:[0,1,1]
	s_or_b64 exec, exec, s[14:15]
